# v85 + G2 K-loop in saddr form (no VALU in its load segments, B-fragment bases in v236/v237)
# speedup vs baseline: 1.0039x; 1.0039x over previous
; template <class Epi>
; __device__ __forceinline__ void gemm_phase(LAS unsigned char* lds, const Gemm g, const StaticOrder& S, const Epi& E, unsigned long long& sw_acc) {
;     ...
;     unsigned voffA[2], voffB[2];
; #pragma unroll
;     for (int i = 0; i < 2; ++i) { int R, C; stage_rc(tid * 16 + i * 8192, R, C);
;         const int Rb = (R >> 5) * 64 + perm32(R & 31);
;         voffA[i] = Epi::A_BLOCKED ? (unsigned)(((R >> 5) * (K >> 3) + (C >> 3)) * 256 + (R & 31) * 8) * 2u : (unsigned)(R * K + C) * 2u; voffB[i] = (unsigned)(Rb * K + C) * 2u; }
;     const size_t kstep = (size_t)(BK * 2);
;     const size_t kstepA = Epi::A_BLOCKED ? (size_t)(BK / 8) * 512 : kstep;
;     const size_t hstep = (size_t)HALF * K * 2;
;     const size_t hstepB = (size_t)32 * K * 2;
;     const size_t tstep = 2 * hstep;
;     const unsigned ldsw = (unsigned)wid * 1024u;
;     const int aoff = lds_byte(wr * 64 + fr, fq * 8), boff = lds_byte(wc * 32 + fr, fq * 8);
.LBB0_685:
	v_bfe_u32 v16, v14, 4, 2
	v_and_b32_e32 v15, 15, v14
	v_lshlrev_b32_e32 v18, 4, v16
	v_lshlrev_b32_e32 v14, 2, v14
	s_and_b32 s36, s10, 3
	v_lshl_or_b32 v187, s1, 6, v15
	v_lshl_or_b32 v15, v15, 6, v18
	s_lshl_b32 s1, s1, 13
	v_and_b32_e32 v14, 32, v14
	s_waitcnt vmcnt(2)
	s_barrier
	s_waitcnt lgkmcnt(0)
	s_add_i32 m0, s30, 0x18000
	v_lshl_add_u64 v[4:5], v[4:5], 0, s[16:17]
	v_bitop3_b32 v18, v15, s1, v14 bitop3:0xde
	s_lshl_b32 s1, s36, 12
	global_load_lds_dwordx4 v[4:5], off
	s_add_i32 m0, s30, 0x1a000
	s_add_u32 s10, s18, 0x1000
	v_mov_b32_e32 v165, v3
	v_lshl_add_u64 v[4:5], v[6:7], 0, s[16:17]
	s_addc_u32 s11, s19, 0
	s_add_i32 s37, s30, 0x8000
	v_mov_b32_e32 v163, v3
	global_load_lds_dwordx4 v[4:5], off
	v_lshl_add_u64 v[4:5], s[10:11], 0, v[164:165]
	s_mov_b32 m0, s37
	s_add_i32 s60, s30, 0xa000
	global_load_lds_dwordx4 v[4:5], off
	v_lshl_add_u64 v[4:5], s[10:11], 0, v[162:163]
	s_add_u32 s10, s6, 0x10080
	s_mov_b32 m0, s60
	s_addc_u32 s11, s7, 0
	global_load_lds_dwordx4 v[4:5], off
	s_add_i32 m0, s30, 0x1c000
	v_lshl_add_u64 v[4:5], s[10:11], 0, v[2:3]
	global_load_lds_dwordx4 v[4:5], off
	v_lshl_add_u64 v[4:5], s[10:11], 0, v[160:161]
	s_add_i32 m0, s30, 0x1e000
	v_lshlrev_b32_e32 v17, 3, v16
	global_load_lds_dwordx4 v[4:5], off
	v_lshlrev_b32_e32 v4, 9, v12
	v_and_b32_e32 v4, 0xffff0000, v4
	v_lshl_add_u32 v4, v11, 9, v4
	v_or_b32_e32 v166, v4, v13
	v_lshlrev_b32_e32 v4, 9, v9
	s_waitcnt vmcnt(6)
	v_and_b32_e32 v4, 0xffff0000, v4
	s_cmpk_lt_u32 s0, 0x100
	v_lshl_add_u32 v4, v8, 9, v4
	v_readlane_b32 s10, v251, 40
	v_bitop3_b32 v200, v15, s1, v14 bitop3:0xde
	v_add_u32_e32 v236, 0x10000, v200
	v_add_u32_e32 v237, 0x18000, v200
	s_cselect_b64 s[46:47], -1, 0
	v_lshl_or_b32 v201, s36, 6, v17
	s_mov_b32 s1, 0
	v_cmp_eq_u32_e64 s[38:39], 0, v16
	v_mov_b32_e32 v167, v3
	v_or_b32_e32 v168, v4, v10
	v_mov_b32_e32 v169, v3
	v_add_u32_e32 v202, 0, v18
	s_mov_b32 s0, s10
	s_barrier
	v_readlane_b32 s11, v251, 41
	s_branch .LBB0_688

; #define PG8_STAGE(bufoff, gbase, voff) do { _Pragma("unroll") for (int _i = 0; _i < 2; ++_i) \
;         __builtin_amdgcn_global_load_lds((const unsigned*)((const char*)(gbase) + (voff)[_i]), (LAS unsigned*)(lds + (bufoff) + ldsw + _i * 8192), 16, 0, 0); } while (0)
; #define PG8_LDA(dst, b, h) do { _Pragma("unroll") for (int m = 0; m < 4; ++m) _Pragma("unroll") for (int k = 0; k < 2; ++k) dst[m][k] = *(const LAS h8*)(lds + PG8_SA(b, h) + aoff + m * 2048 + k * 1024); } while (0)
; #define PG8_LDB(dst, b, h) do { _Pragma("unroll") for (int n = 0; n < 2; ++n) _Pragma("unroll") for (int k = 0; k < 2; ++k) dst[n][k] = *(const LAS h8*)(lds + PG8_SB(b, h) + boff + n * 2048 + k * 1024); } while (0)
; #define PG8_MMA(ai, bj, At, Bt) do { __builtin_amdgcn_s_setprio(1); _Pragma("unroll") for (int m = 0; m < 4; ++m) _Pragma("unroll") for (int n = 0; n < 2; ++n) _Pragma("unroll") for (int k = 0; k < 2; ++k) \
;         acc[ai][bj][m][n] = __builtin_amdgcn_mfma_f32_16x16x32_f16(Bt[n][k], At[m][k], acc[ai][bj][m][n], 0, 0, 0); __builtin_amdgcn_s_setprio(0); } while (0)
; #define PG8_WAIT_V(n) asm volatile("s_waitcnt vmcnt(" #n ")" ::: "memory")
; #define PG8_WAIT_L(n) asm volatile("s_waitcnt lgkmcnt(" #n ")" ::: "memory")
; #define PG8_BAR __builtin_amdgcn_s_barrier()
; #define PG8_SCHED __builtin_amdgcn_sched_barrier(0)
; template <class Epi>
; __device__ __forceinline__ void gemm_phase(LAS unsigned char* lds, const Gemm g, const StaticOrder& S, const Epi& E, unsigned long long& sw_acc) {
;     ...
;             const char* a1 = cA + (size_t)(t + 1) * kstepA;
;             const char* a2 = last ? nA : cA + (size_t)(t + 2) * kstepA; const char* b2 = last ? nB : cB + (size_t)(t + 2) * kstep;
;             const char* a3 = a2 + kstepA; const char* b3 = b2 + kstep;
;             PG8_LDB(B0, 0, 0); PG8_LDB(B1, 0, 1); PG8_SCHED; PG8_LDA(At, 0, 0); PG8_STAGE(PG8_SA(1, 1), a1 + hstep, voffA);
;             PG8_WAIT_V(8); PG8_WAIT_L(0); PG8_BAR; PG8_MMA(0, 0, At, B0); PG8_MMA(0, 1, At, B1); PG8_BAR; PG8_SCHED;
;             PG8_LDA(At, 0, 1); PG8_STAGE(PG8_SB(0, 0), b2, voffB); PG8_STAGE(PG8_SB(0, 1), b2 + hstepB, voffB); PG8_STAGE(PG8_SA(0, 0), a2, voffA);
;             PG8_WAIT_V(8); PG8_WAIT_L(0); PG8_BAR; PG8_MMA(1, 0, At, B0); PG8_MMA(1, 1, At, B1); PG8_BAR; PG8_SCHED;
.Lg2z_peel:
	s_add_u32 s18, s6, 0xfffc1000
	s_addc_u32 s19, s7, -1
	s_cmp_eq_u32 s22, 12
	s_cselect_b32 s24, s5, s18
	s_cselect_b32 s25, s1, s19
	s_cselect_b32 s20, s11, s14
	s_cselect_b32 s21, s10, s15
	s_add_u32 s18, s24, 0x1000
	s_addc_u32 s19, s25, 0
	s_add_i32 s23, 0, 0x10000
	s_add_i32 s42, 0, 0x14000
	ds_read_b128 v[124:127], v236
	ds_read_b128 v[136:139], v236 offset:1024
	ds_read_b128 v[140:143], v236 offset:2048
	ds_read_b128 v[144:147], v236 offset:3072
	ds_read_b128 v[148:151], v236 offset:16384
	ds_read_b128 v[152:155], v236 offset:17408
	ds_read_b128 v[156:159], v236 offset:18432
	ds_read_b128 v[170:173], v236 offset:19456
	s_add_i32 m0, s30, 0xc000
	ds_read_b128 v[174:177], v202
	ds_read_b128 v[192:195], v202 offset:1024
	ds_read_b128 v[196:199], v202 offset:2048
	ds_read_b128 v[204:207], v202 offset:3072
	ds_read_b128 v[218:221], v202 offset:4096
	ds_read_b128 v[222:225], v202 offset:5120
	ds_read_b128 v[226:229], v202 offset:6144
	ds_read_b128 v[230:233], v202 offset:7168
	global_load_lds_dwordx4 v166, s[6:7]
	s_add_i32 m0, s30, 0xe000
	s_nop 0
	global_load_lds_dwordx4 v168, s[6:7]
	s_waitcnt vmcnt(8)
	s_waitcnt lgkmcnt(0)
	s_barrier
	s_waitcnt lgkmcnt(0)
	v_mfma_f32_16x16x32_f16 v[132:135], v[124:127], v[174:177], 0
	v_mfma_f32_16x16x32_f16 v[128:131], v[140:143], v[174:177], 0
	v_mfma_f32_16x16x32_f16 v[112:115], v[124:127], v[196:199], 0
	v_mfma_f32_16x16x32_f16 v[108:111], v[140:143], v[196:199], 0
	v_mfma_f32_16x16x32_f16 v[96:99], v[124:127], v[218:221], 0
	v_mfma_f32_16x16x32_f16 v[92:95], v[140:143], v[218:221], 0
	v_mfma_f32_16x16x32_f16 v[80:83], v[124:127], v[226:229], 0
	v_mfma_f32_16x16x32_f16 v[76:79], v[140:143], v[226:229], 0
	v_mfma_f32_16x16x32_f16 v[132:135], v[136:139], v[192:195], v[132:135]
	v_mfma_f32_16x16x32_f16 v[128:131], v[144:147], v[192:195], v[128:131]
	v_mfma_f32_16x16x32_f16 v[112:115], v[136:139], v[204:207], v[112:115]
	v_mfma_f32_16x16x32_f16 v[108:111], v[144:147], v[204:207], v[108:111]
	v_mfma_f32_16x16x32_f16 v[96:99], v[136:139], v[222:225], v[96:99]
	v_mfma_f32_16x16x32_f16 v[92:95], v[144:147], v[222:225], v[92:95]
	v_mfma_f32_16x16x32_f16 v[80:83], v[136:139], v[230:233], v[80:83]
	v_mfma_f32_16x16x32_f16 v[76:79], v[144:147], v[230:233], v[76:79]
	v_mfma_f32_16x16x32_f16 v[120:123], v[148:151], v[174:177], 0
	v_mfma_f32_16x16x32_f16 v[116:119], v[156:159], v[174:177], 0
	v_mfma_f32_16x16x32_f16 v[104:107], v[148:151], v[196:199], 0
	v_mfma_f32_16x16x32_f16 v[100:103], v[156:159], v[196:199], 0
	v_mfma_f32_16x16x32_f16 v[88:91], v[148:151], v[218:221], 0
	v_mfma_f32_16x16x32_f16 v[84:87], v[156:159], v[218:221], 0
	v_mfma_f32_16x16x32_f16 v[72:75], v[148:151], v[226:229], 0
	v_mfma_f32_16x16x32_f16 v[68:71], v[156:159], v[226:229], 0
	v_mfma_f32_16x16x32_f16 v[120:123], v[152:155], v[192:195], v[120:123]
	v_mfma_f32_16x16x32_f16 v[116:119], v[170:173], v[192:195], v[116:119]
	v_mfma_f32_16x16x32_f16 v[104:107], v[152:155], v[204:207], v[104:107]
	v_mfma_f32_16x16x32_f16 v[100:103], v[170:173], v[204:207], v[100:103]
	v_mfma_f32_16x16x32_f16 v[88:91], v[152:155], v[222:225], v[88:91]
	v_mfma_f32_16x16x32_f16 v[84:87], v[170:173], v[222:225], v[84:87]
	v_mfma_f32_16x16x32_f16 v[72:75], v[152:155], v[230:233], v[72:75]
	v_mfma_f32_16x16x32_f16 v[68:71], v[170:173], v[230:233], v[68:71]
	s_barrier
	s_add_i32 s23, s23, s29
	s_mov_b32 m0, s23
	ds_read_b128 v[174:177], v202 offset:16384
	ds_read_b128 v[192:195], v202 offset:17408
	ds_read_b128 v[196:199], v202 offset:18432
	ds_read_b128 v[204:207], v202 offset:19456
	ds_read_b128 v[218:221], v202 offset:20480
	ds_read_b128 v[222:225], v202 offset:21504
	ds_read_b128 v[226:229], v202 offset:22528
	ds_read_b128 v[230:233], v202 offset:23552
	global_load_lds_dwordx4 v2, s[20:21]
	s_add_i32 m0, s23, 0x2000
	s_add_u32 s40, s20, 0x10000
	s_addc_u32 s41, s21, 0
	s_add_i32 s23, s42, s29
	global_load_lds_dwordx4 v160, s[20:21]
	s_mov_b32 m0, s23
	s_nop 0
	global_load_lds_dwordx4 v2, s[40:41]
	s_add_i32 m0, s23, 0x2000
	s_nop 0
	global_load_lds_dwordx4 v160, s[40:41]
	s_mov_b32 m0, s30
	s_nop 0
	global_load_lds_dwordx4 v164, s[24:25]
	s_mov_b32 m0, s31
	s_nop 0
	global_load_lds_dwordx4 v162, s[24:25]
	s_waitcnt vmcnt(8)
	s_waitcnt lgkmcnt(0)
	s_barrier
	s_waitcnt lgkmcnt(0)
	v_mfma_f32_16x16x32_f16 v[64:67], v[124:127], v[174:177], 0
	v_mfma_f32_16x16x32_f16 v[60:63], v[140:143], v[174:177], 0
	v_mfma_f32_16x16x32_f16 v[48:51], v[124:127], v[196:199], 0
	v_mfma_f32_16x16x32_f16 v[44:47], v[140:143], v[196:199], 0
	v_mfma_f32_16x16x32_f16 v[32:35], v[124:127], v[218:221], 0
	v_mfma_f32_16x16x32_f16 v[28:31], v[140:143], v[218:221], 0
	v_mfma_f32_16x16x32_f16 v[16:19], v[124:127], v[226:229], 0
	v_mfma_f32_16x16x32_f16 v[12:15], v[140:143], v[226:229], 0
	v_mfma_f32_16x16x32_f16 v[64:67], v[136:139], v[192:195], v[64:67]
	v_mfma_f32_16x16x32_f16 v[60:63], v[144:147], v[192:195], v[60:63]
	v_mfma_f32_16x16x32_f16 v[48:51], v[136:139], v[204:207], v[48:51]
	v_mfma_f32_16x16x32_f16 v[44:47], v[144:147], v[204:207], v[44:47]
	v_mfma_f32_16x16x32_f16 v[32:35], v[136:139], v[222:225], v[32:35]
	v_mfma_f32_16x16x32_f16 v[28:31], v[144:147], v[222:225], v[28:31]
	v_mfma_f32_16x16x32_f16 v[16:19], v[136:139], v[230:233], v[16:19]
	v_mfma_f32_16x16x32_f16 v[12:15], v[144:147], v[230:233], v[12:15]
	v_mfma_f32_16x16x32_f16 v[56:59], v[148:151], v[174:177], 0
	v_mfma_f32_16x16x32_f16 v[52:55], v[156:159], v[174:177], 0
	v_mfma_f32_16x16x32_f16 v[40:43], v[148:151], v[196:199], 0
	v_mfma_f32_16x16x32_f16 v[36:39], v[156:159], v[196:199], 0
	v_mfma_f32_16x16x32_f16 v[24:27], v[148:151], v[218:221], 0
	v_mfma_f32_16x16x32_f16 v[20:23], v[156:159], v[218:221], 0
	v_mfma_f32_16x16x32_f16 v[8:11], v[148:151], v[226:229], 0
	v_mfma_f32_16x16x32_f16 v[4:7], v[156:159], v[226:229], 0
	v_mfma_f32_16x16x32_f16 v[56:59], v[152:155], v[192:195], v[56:59]
	v_mfma_f32_16x16x32_f16 v[52:55], v[170:173], v[192:195], v[52:55]
	v_mfma_f32_16x16x32_f16 v[40:43], v[152:155], v[204:207], v[40:43]
	v_mfma_f32_16x16x32_f16 v[36:39], v[170:173], v[204:207], v[36:39]
	v_mfma_f32_16x16x32_f16 v[24:27], v[152:155], v[222:225], v[24:27]
	v_mfma_f32_16x16x32_f16 v[20:23], v[170:173], v[222:225], v[20:23]
	v_mfma_f32_16x16x32_f16 v[8:11], v[152:155], v[230:233], v[8:11]
	v_mfma_f32_16x16x32_f16 v[4:7], v[170:173], v[230:233], v[4:7]
	s_barrier
	s_branch .Lg2z_mid
; #define PG8_STAGE(bufoff, gbase, voff) do { _Pragma("unroll") for (int _i = 0; _i < 2; ++_i) \
;         __builtin_amdgcn_global_load_lds((const unsigned*)((const char*)(gbase) + (voff)[_i]), (LAS unsigned*)(lds + (bufoff) + ldsw + _i * 8192), 16, 0, 0); } while (0)
; #define PG8_LDA(dst, b, h) do { _Pragma("unroll") for (int m = 0; m < 4; ++m) _Pragma("unroll") for (int k = 0; k < 2; ++k) dst[m][k] = *(const LAS h8*)(lds + PG8_SA(b, h) + aoff + m * 2048 + k * 1024); } while (0)
; #define PG8_LDB(dst, b, h) do { _Pragma("unroll") for (int n = 0; n < 2; ++n) _Pragma("unroll") for (int k = 0; k < 2; ++k) dst[n][k] = *(const LAS h8*)(lds + PG8_SB(b, h) + boff + n * 2048 + k * 1024); } while (0)
; #define PG8_MMA(ai, bj, At, Bt) do { __builtin_amdgcn_s_setprio(1); _Pragma("unroll") for (int m = 0; m < 4; ++m) _Pragma("unroll") for (int n = 0; n < 2; ++n) _Pragma("unroll") for (int k = 0; k < 2; ++k) \
;         acc[ai][bj][m][n] = __builtin_amdgcn_mfma_f32_16x16x32_f16(Bt[n][k], At[m][k], acc[ai][bj][m][n], 0, 0, 0); __builtin_amdgcn_s_setprio(0); } while (0)
; #define PG8_WAIT_V(n) asm volatile("s_waitcnt vmcnt(" #n ")" ::: "memory")
; #define PG8_WAIT_L(n) asm volatile("s_waitcnt lgkmcnt(" #n ")" ::: "memory")
; #define PG8_BAR __builtin_amdgcn_s_barrier()
; #define PG8_SCHED __builtin_amdgcn_sched_barrier(0)
; template <class Epi>
; __device__ __forceinline__ void gemm_phase(LAS unsigned char* lds, const Gemm g, const StaticOrder& S, const Epi& E, unsigned long long& sw_acc) {
;     ...
;             PG8_LDB(B0, 0, 0); PG8_LDB(B1, 0, 1); PG8_SCHED; PG8_LDA(At, 0, 0); PG8_STAGE(PG8_SA(1, 1), a1 + hstep, voffA);
;             PG8_WAIT_V(8); PG8_WAIT_L(0); PG8_BAR; PG8_MMA(0, 0, At, B0); PG8_MMA(0, 1, At, B1); PG8_BAR; PG8_SCHED;
;             PG8_LDA(At, 0, 1); PG8_STAGE(PG8_SB(0, 0), b2, voffB); PG8_STAGE(PG8_SB(0, 1), b2 + hstepB, voffB); PG8_STAGE(PG8_SA(0, 0), a2, voffA);
;             PG8_WAIT_V(8); PG8_WAIT_L(0); PG8_BAR; PG8_MMA(1, 0, At, B0); PG8_MMA(1, 1, At, B1); PG8_BAR; PG8_SCHED;
.LBB0_700:
	s_add_u32 s18, s6, 0xfffc1000
	s_addc_u32 s19, s7, -1
	s_cmp_eq_u32 s22, 12
	s_cselect_b32 s24, s5, s18
	s_cselect_b32 s25, s1, s19
	s_cselect_b32 s20, s11, s14
	s_cselect_b32 s21, s10, s15
	s_add_u32 s18, s24, 0x1000
	s_addc_u32 s19, s25, 0
	s_add_i32 s23, 0, 0x10000
	s_add_i32 s42, 0, 0x14000
	ds_read_b128 v[124:127], v236
	ds_read_b128 v[136:139], v236 offset:1024
	ds_read_b128 v[140:143], v236 offset:2048
	ds_read_b128 v[144:147], v236 offset:3072
	ds_read_b128 v[148:151], v236 offset:16384
	ds_read_b128 v[152:155], v236 offset:17408
	ds_read_b128 v[156:159], v236 offset:18432
	ds_read_b128 v[170:173], v236 offset:19456
	s_add_i32 m0, s30, 0xc000
	ds_read_b128 v[174:177], v202
	ds_read_b128 v[192:195], v202 offset:1024
	ds_read_b128 v[196:199], v202 offset:2048
	ds_read_b128 v[204:207], v202 offset:3072
	ds_read_b128 v[218:221], v202 offset:4096
	ds_read_b128 v[222:225], v202 offset:5120
	ds_read_b128 v[226:229], v202 offset:6144
	ds_read_b128 v[230:233], v202 offset:7168
	global_load_lds_dwordx4 v166, s[6:7]
	s_add_i32 m0, s30, 0xe000
	s_nop 0
	global_load_lds_dwordx4 v168, s[6:7]
	s_waitcnt vmcnt(8)
	s_waitcnt lgkmcnt(0)
	s_barrier
	s_waitcnt lgkmcnt(0)
	v_mfma_f32_16x16x32_f16 v[132:135], v[124:127], v[174:177], v[132:135]
	v_mfma_f32_16x16x32_f16 v[128:131], v[140:143], v[174:177], v[128:131]
	v_mfma_f32_16x16x32_f16 v[112:115], v[124:127], v[196:199], v[112:115]
	v_mfma_f32_16x16x32_f16 v[108:111], v[140:143], v[196:199], v[108:111]
	v_mfma_f32_16x16x32_f16 v[96:99], v[124:127], v[218:221], v[96:99]
	v_mfma_f32_16x16x32_f16 v[92:95], v[140:143], v[218:221], v[92:95]
	v_mfma_f32_16x16x32_f16 v[80:83], v[124:127], v[226:229], v[80:83]
	v_mfma_f32_16x16x32_f16 v[76:79], v[140:143], v[226:229], v[76:79]
	v_mfma_f32_16x16x32_f16 v[132:135], v[136:139], v[192:195], v[132:135]
	v_mfma_f32_16x16x32_f16 v[128:131], v[144:147], v[192:195], v[128:131]
	v_mfma_f32_16x16x32_f16 v[112:115], v[136:139], v[204:207], v[112:115]
	v_mfma_f32_16x16x32_f16 v[108:111], v[144:147], v[204:207], v[108:111]
	v_mfma_f32_16x16x32_f16 v[96:99], v[136:139], v[222:225], v[96:99]
	v_mfma_f32_16x16x32_f16 v[92:95], v[144:147], v[222:225], v[92:95]
	v_mfma_f32_16x16x32_f16 v[80:83], v[136:139], v[230:233], v[80:83]
	v_mfma_f32_16x16x32_f16 v[76:79], v[144:147], v[230:233], v[76:79]
	v_mfma_f32_16x16x32_f16 v[120:123], v[148:151], v[174:177], v[120:123]
	v_mfma_f32_16x16x32_f16 v[116:119], v[156:159], v[174:177], v[116:119]
	v_mfma_f32_16x16x32_f16 v[104:107], v[148:151], v[196:199], v[104:107]
	v_mfma_f32_16x16x32_f16 v[100:103], v[156:159], v[196:199], v[100:103]
	v_mfma_f32_16x16x32_f16 v[88:91], v[148:151], v[218:221], v[88:91]
	v_mfma_f32_16x16x32_f16 v[84:87], v[156:159], v[218:221], v[84:87]
	v_mfma_f32_16x16x32_f16 v[72:75], v[148:151], v[226:229], v[72:75]
	v_mfma_f32_16x16x32_f16 v[68:71], v[156:159], v[226:229], v[68:71]
	v_mfma_f32_16x16x32_f16 v[120:123], v[152:155], v[192:195], v[120:123]
	v_mfma_f32_16x16x32_f16 v[116:119], v[170:173], v[192:195], v[116:119]
	v_mfma_f32_16x16x32_f16 v[104:107], v[152:155], v[204:207], v[104:107]
	v_mfma_f32_16x16x32_f16 v[100:103], v[170:173], v[204:207], v[100:103]
	v_mfma_f32_16x16x32_f16 v[88:91], v[152:155], v[222:225], v[88:91]
	v_mfma_f32_16x16x32_f16 v[84:87], v[170:173], v[222:225], v[84:87]
	v_mfma_f32_16x16x32_f16 v[72:75], v[152:155], v[230:233], v[72:75]
	v_mfma_f32_16x16x32_f16 v[68:71], v[170:173], v[230:233], v[68:71]
	s_barrier
	s_add_i32 s23, s23, s29
	s_mov_b32 m0, s23
	ds_read_b128 v[174:177], v202 offset:16384
	ds_read_b128 v[192:195], v202 offset:17408
	ds_read_b128 v[196:199], v202 offset:18432
	ds_read_b128 v[204:207], v202 offset:19456
	ds_read_b128 v[218:221], v202 offset:20480
	ds_read_b128 v[222:225], v202 offset:21504
	ds_read_b128 v[226:229], v202 offset:22528
	ds_read_b128 v[230:233], v202 offset:23552
	global_load_lds_dwordx4 v2, s[20:21]
	s_add_i32 m0, s23, 0x2000
	s_add_u32 s40, s20, 0x10000
	s_addc_u32 s41, s21, 0
	s_add_i32 s23, s42, s29
	global_load_lds_dwordx4 v160, s[20:21]
	s_mov_b32 m0, s23
	s_nop 0
	global_load_lds_dwordx4 v2, s[40:41]
	s_add_i32 m0, s23, 0x2000
	s_nop 0
	global_load_lds_dwordx4 v160, s[40:41]
	s_mov_b32 m0, s30
	s_nop 0
	global_load_lds_dwordx4 v164, s[24:25]
	s_mov_b32 m0, s31
	s_nop 0
	global_load_lds_dwordx4 v162, s[24:25]
	s_waitcnt vmcnt(8)
	s_waitcnt lgkmcnt(0)
	s_barrier
	s_waitcnt lgkmcnt(0)
	v_mfma_f32_16x16x32_f16 v[64:67], v[124:127], v[174:177], v[64:67]
	v_mfma_f32_16x16x32_f16 v[60:63], v[140:143], v[174:177], v[60:63]
	v_mfma_f32_16x16x32_f16 v[48:51], v[124:127], v[196:199], v[48:51]
	v_mfma_f32_16x16x32_f16 v[44:47], v[140:143], v[196:199], v[44:47]
	v_mfma_f32_16x16x32_f16 v[32:35], v[124:127], v[218:221], v[32:35]
	v_mfma_f32_16x16x32_f16 v[28:31], v[140:143], v[218:221], v[28:31]
	v_mfma_f32_16x16x32_f16 v[16:19], v[124:127], v[226:229], v[16:19]
	v_mfma_f32_16x16x32_f16 v[12:15], v[140:143], v[226:229], v[12:15]
	v_mfma_f32_16x16x32_f16 v[64:67], v[136:139], v[192:195], v[64:67]
	v_mfma_f32_16x16x32_f16 v[60:63], v[144:147], v[192:195], v[60:63]
	v_mfma_f32_16x16x32_f16 v[48:51], v[136:139], v[204:207], v[48:51]
	v_mfma_f32_16x16x32_f16 v[44:47], v[144:147], v[204:207], v[44:47]
	v_mfma_f32_16x16x32_f16 v[32:35], v[136:139], v[222:225], v[32:35]
	v_mfma_f32_16x16x32_f16 v[28:31], v[144:147], v[222:225], v[28:31]
	v_mfma_f32_16x16x32_f16 v[16:19], v[136:139], v[230:233], v[16:19]
	v_mfma_f32_16x16x32_f16 v[12:15], v[144:147], v[230:233], v[12:15]
	v_mfma_f32_16x16x32_f16 v[56:59], v[148:151], v[174:177], v[56:59]
	v_mfma_f32_16x16x32_f16 v[52:55], v[156:159], v[174:177], v[52:55]
	v_mfma_f32_16x16x32_f16 v[40:43], v[148:151], v[196:199], v[40:43]
	v_mfma_f32_16x16x32_f16 v[36:39], v[156:159], v[196:199], v[36:39]
	v_mfma_f32_16x16x32_f16 v[24:27], v[148:151], v[218:221], v[24:27]
	v_mfma_f32_16x16x32_f16 v[20:23], v[156:159], v[218:221], v[20:23]
	v_mfma_f32_16x16x32_f16 v[8:11], v[148:151], v[226:229], v[8:11]
	v_mfma_f32_16x16x32_f16 v[4:7], v[156:159], v[226:229], v[4:7]
	v_mfma_f32_16x16x32_f16 v[56:59], v[152:155], v[192:195], v[56:59]
	v_mfma_f32_16x16x32_f16 v[52:55], v[170:173], v[192:195], v[52:55]
	v_mfma_f32_16x16x32_f16 v[40:43], v[152:155], v[204:207], v[40:43]
	v_mfma_f32_16x16x32_f16 v[36:39], v[170:173], v[204:207], v[36:39]
	v_mfma_f32_16x16x32_f16 v[24:27], v[152:155], v[222:225], v[24:27]
	v_mfma_f32_16x16x32_f16 v[20:23], v[170:173], v[222:225], v[20:23]
	v_mfma_f32_16x16x32_f16 v[8:11], v[152:155], v[230:233], v[8:11]
	v_mfma_f32_16x16x32_f16 v[4:7], v[170:173], v[230:233], v[4:7]
	s_barrier
; #define PG8_STAGE(bufoff, gbase, voff) do { _Pragma("unroll") for (int _i = 0; _i < 2; ++_i) \
;         __builtin_amdgcn_global_load_lds((const unsigned*)((const char*)(gbase) + (voff)[_i]), (LAS unsigned*)(lds + (bufoff) + ldsw + _i * 8192), 16, 0, 0); } while (0)
; #define PG8_LDA(dst, b, h) do { _Pragma("unroll") for (int m = 0; m < 4; ++m) _Pragma("unroll") for (int k = 0; k < 2; ++k) dst[m][k] = *(const LAS h8*)(lds + PG8_SA(b, h) + aoff + m * 2048 + k * 1024); } while (0)
; #define PG8_LDB(dst, b, h) do { _Pragma("unroll") for (int n = 0; n < 2; ++n) _Pragma("unroll") for (int k = 0; k < 2; ++k) dst[n][k] = *(const LAS h8*)(lds + PG8_SB(b, h) + boff + n * 2048 + k * 1024); } while (0)
; #define PG8_MMA(ai, bj, At, Bt) do { __builtin_amdgcn_s_setprio(1); _Pragma("unroll") for (int m = 0; m < 4; ++m) _Pragma("unroll") for (int n = 0; n < 2; ++n) _Pragma("unroll") for (int k = 0; k < 2; ++k) \
;         acc[ai][bj][m][n] = __builtin_amdgcn_mfma_f32_16x16x32_f16(Bt[n][k], At[m][k], acc[ai][bj][m][n], 0, 0, 0); __builtin_amdgcn_s_setprio(0); } while (0)
; #define PG8_WAIT_V(n) asm volatile("s_waitcnt vmcnt(" #n ")" ::: "memory")
; #define PG8_WAIT_L(n) asm volatile("s_waitcnt lgkmcnt(" #n ")" ::: "memory")
; #define PG8_BAR __builtin_amdgcn_s_barrier()
; #define PG8_SCHED __builtin_amdgcn_sched_barrier(0)
; template <class Epi>
; __device__ __forceinline__ void gemm_phase(LAS unsigned char* lds, const Gemm g, const StaticOrder& S, const Epi& E, unsigned long long& sw_acc) {
;     ...
;             PG8_LDB(B0, 1, 0); PG8_LDB(B1, 1, 1); PG8_SCHED; PG8_LDA(At, 1, 0); PG8_STAGE(PG8_SA(0, 1), a2 + hstep, voffA);
;             PG8_WAIT_V(8); PG8_WAIT_L(0); PG8_BAR; PG8_MMA(0, 0, At, B0); PG8_MMA(0, 1, At, B1); PG8_BAR; PG8_SCHED;
;             PG8_LDA(At, 1, 1); PG8_STAGE(PG8_SB(1, 0), b3, voffB); PG8_STAGE(PG8_SB(1, 1), b3 + hstepB, voffB); PG8_STAGE(PG8_SA(1, 0), a3, voffA);
;             PG8_WAIT_V(8); PG8_WAIT_L(0); PG8_BAR; PG8_MMA(1, 0, At, B0); PG8_MMA(1, 1, At, B1); PG8_BAR; PG8_SCHED;
;         }
.Lg2z_mid:
	s_add_i32 s23, 0, 0x18000
	s_add_i32 s40, 0, 0x1c000
	ds_read_b128 v[124:127], v237
	ds_read_b128 v[136:139], v237 offset:1024
	ds_read_b128 v[140:143], v237 offset:2048
	ds_read_b128 v[144:147], v237 offset:3072
	ds_read_b128 v[148:151], v237 offset:16384
	ds_read_b128 v[152:155], v237 offset:17408
	ds_read_b128 v[156:159], v237 offset:18432
	ds_read_b128 v[170:173], v237 offset:19456
	s_add_u32 s24, s24, 0x40000
	s_addc_u32 s25, s25, 0
	s_mov_b32 m0, s34
	ds_read_b128 v[174:177], v202 offset:32768
	ds_read_b128 v[192:195], v202 offset:33792
	ds_read_b128 v[196:199], v202 offset:34816
	ds_read_b128 v[204:207], v202 offset:35840
	ds_read_b128 v[218:221], v202 offset:36864
	ds_read_b128 v[222:225], v202 offset:37888
	ds_read_b128 v[226:229], v202 offset:38912
	ds_read_b128 v[230:233], v202 offset:39936
	global_load_lds_dwordx4 v164, s[24:25]
	s_mov_b32 m0, s35
	s_nop 0
	global_load_lds_dwordx4 v162, s[24:25]
	s_waitcnt vmcnt(8)
	s_waitcnt lgkmcnt(0)
	s_barrier
	s_waitcnt lgkmcnt(0)
	v_mfma_f32_16x16x32_f16 v[132:135], v[124:127], v[174:177], v[132:135]
	v_mfma_f32_16x16x32_f16 v[128:131], v[140:143], v[174:177], v[128:131]
	v_mfma_f32_16x16x32_f16 v[112:115], v[124:127], v[196:199], v[112:115]
	v_mfma_f32_16x16x32_f16 v[108:111], v[140:143], v[196:199], v[108:111]
	v_mfma_f32_16x16x32_f16 v[96:99], v[124:127], v[218:221], v[96:99]
	v_mfma_f32_16x16x32_f16 v[92:95], v[140:143], v[218:221], v[92:95]
	v_mfma_f32_16x16x32_f16 v[80:83], v[124:127], v[226:229], v[80:83]
	v_mfma_f32_16x16x32_f16 v[76:79], v[140:143], v[226:229], v[76:79]
	v_mfma_f32_16x16x32_f16 v[132:135], v[136:139], v[192:195], v[132:135]
	v_mfma_f32_16x16x32_f16 v[128:131], v[144:147], v[192:195], v[128:131]
	v_mfma_f32_16x16x32_f16 v[112:115], v[136:139], v[204:207], v[112:115]
	v_mfma_f32_16x16x32_f16 v[108:111], v[144:147], v[204:207], v[108:111]
	v_mfma_f32_16x16x32_f16 v[96:99], v[136:139], v[222:225], v[96:99]
	v_mfma_f32_16x16x32_f16 v[92:95], v[144:147], v[222:225], v[92:95]
	v_mfma_f32_16x16x32_f16 v[80:83], v[136:139], v[230:233], v[80:83]
	v_mfma_f32_16x16x32_f16 v[76:79], v[144:147], v[230:233], v[76:79]
	v_mfma_f32_16x16x32_f16 v[120:123], v[148:151], v[174:177], v[120:123]
	v_mfma_f32_16x16x32_f16 v[116:119], v[156:159], v[174:177], v[116:119]
	v_mfma_f32_16x16x32_f16 v[104:107], v[148:151], v[196:199], v[104:107]
	v_mfma_f32_16x16x32_f16 v[100:103], v[156:159], v[196:199], v[100:103]
	v_mfma_f32_16x16x32_f16 v[88:91], v[148:151], v[218:221], v[88:91]
	v_mfma_f32_16x16x32_f16 v[84:87], v[156:159], v[218:221], v[84:87]
	v_mfma_f32_16x16x32_f16 v[72:75], v[148:151], v[226:229], v[72:75]
	v_mfma_f32_16x16x32_f16 v[68:71], v[156:159], v[226:229], v[68:71]
	v_mfma_f32_16x16x32_f16 v[120:123], v[152:155], v[192:195], v[120:123]
	v_mfma_f32_16x16x32_f16 v[116:119], v[170:173], v[192:195], v[116:119]
	v_mfma_f32_16x16x32_f16 v[104:107], v[152:155], v[204:207], v[104:107]
	v_mfma_f32_16x16x32_f16 v[100:103], v[170:173], v[204:207], v[100:103]
	v_mfma_f32_16x16x32_f16 v[88:91], v[152:155], v[222:225], v[88:91]
	v_mfma_f32_16x16x32_f16 v[84:87], v[170:173], v[222:225], v[84:87]
	v_mfma_f32_16x16x32_f16 v[72:75], v[152:155], v[230:233], v[72:75]
	v_mfma_f32_16x16x32_f16 v[68:71], v[170:173], v[230:233], v[68:71]
	s_barrier
	s_add_i32 s23, s23, s29
	s_add_u32 s20, s20, 0x80
	s_addc_u32 s21, s21, 0
	s_mov_b32 m0, s23
	ds_read_b128 v[174:177], v202 offset:49152
	ds_read_b128 v[192:195], v202 offset:50176
	ds_read_b128 v[196:199], v202 offset:51200
	ds_read_b128 v[204:207], v202 offset:52224
	ds_read_b128 v[218:221], v202 offset:53248
	ds_read_b128 v[222:225], v202 offset:54272
	ds_read_b128 v[226:229], v202 offset:55296
	ds_read_b128 v[230:233], v202 offset:56320
	global_load_lds_dwordx4 v2, s[20:21]
	s_add_i32 m0, s23, 0x2000
	s_add_i32 s23, s40, s29
	global_load_lds_dwordx4 v160, s[20:21]
	s_add_u32 s20, s20, 0x10000
	s_addc_u32 s21, s21, 0
	s_mov_b32 m0, s23
	s_nop 0
	global_load_lds_dwordx4 v2, s[20:21]
	s_add_i32 m0, s23, 0x2000
	s_nop 0
	global_load_lds_dwordx4 v160, s[20:21]
	s_mov_b32 m0, s37
	s_nop 0
	global_load_lds_dwordx4 v164, s[18:19]
	s_mov_b32 m0, s60
	s_nop 0
	global_load_lds_dwordx4 v162, s[18:19]
	s_waitcnt vmcnt(8)
	s_waitcnt lgkmcnt(0)
	s_barrier
	s_waitcnt lgkmcnt(0)
	v_mfma_f32_16x16x32_f16 v[64:67], v[124:127], v[174:177], v[64:67]
	v_mfma_f32_16x16x32_f16 v[60:63], v[140:143], v[174:177], v[60:63]
	v_mfma_f32_16x16x32_f16 v[48:51], v[124:127], v[196:199], v[48:51]
	v_mfma_f32_16x16x32_f16 v[44:47], v[140:143], v[196:199], v[44:47]
	v_mfma_f32_16x16x32_f16 v[32:35], v[124:127], v[218:221], v[32:35]
	v_mfma_f32_16x16x32_f16 v[28:31], v[140:143], v[218:221], v[28:31]
	v_mfma_f32_16x16x32_f16 v[16:19], v[124:127], v[226:229], v[16:19]
	v_mfma_f32_16x16x32_f16 v[12:15], v[140:143], v[226:229], v[12:15]
	v_mfma_f32_16x16x32_f16 v[64:67], v[136:139], v[192:195], v[64:67]
	v_mfma_f32_16x16x32_f16 v[60:63], v[144:147], v[192:195], v[60:63]
	v_mfma_f32_16x16x32_f16 v[48:51], v[136:139], v[204:207], v[48:51]
	v_mfma_f32_16x16x32_f16 v[44:47], v[144:147], v[204:207], v[44:47]
	v_mfma_f32_16x16x32_f16 v[32:35], v[136:139], v[222:225], v[32:35]
	v_mfma_f32_16x16x32_f16 v[28:31], v[144:147], v[222:225], v[28:31]
	v_mfma_f32_16x16x32_f16 v[16:19], v[136:139], v[230:233], v[16:19]
	v_mfma_f32_16x16x32_f16 v[12:15], v[144:147], v[230:233], v[12:15]
	v_mfma_f32_16x16x32_f16 v[56:59], v[148:151], v[174:177], v[56:59]
	v_mfma_f32_16x16x32_f16 v[52:55], v[156:159], v[174:177], v[52:55]
	v_mfma_f32_16x16x32_f16 v[40:43], v[148:151], v[196:199], v[40:43]
	v_mfma_f32_16x16x32_f16 v[36:39], v[156:159], v[196:199], v[36:39]
	v_mfma_f32_16x16x32_f16 v[24:27], v[148:151], v[218:221], v[24:27]
	v_mfma_f32_16x16x32_f16 v[20:23], v[156:159], v[218:221], v[20:23]
	v_mfma_f32_16x16x32_f16 v[8:11], v[148:151], v[226:229], v[8:11]
	v_mfma_f32_16x16x32_f16 v[4:7], v[156:159], v[226:229], v[4:7]
	v_mfma_f32_16x16x32_f16 v[56:59], v[152:155], v[192:195], v[56:59]
	v_mfma_f32_16x16x32_f16 v[52:55], v[170:173], v[192:195], v[52:55]
	v_mfma_f32_16x16x32_f16 v[40:43], v[152:155], v[204:207], v[40:43]
	v_mfma_f32_16x16x32_f16 v[36:39], v[170:173], v[204:207], v[36:39]
	v_mfma_f32_16x16x32_f16 v[24:27], v[152:155], v[222:225], v[24:27]
	v_mfma_f32_16x16x32_f16 v[20:23], v[170:173], v[222:225], v[20:23]
	v_mfma_f32_16x16x32_f16 v[8:11], v[152:155], v[230:233], v[8:11]
	v_mfma_f32_16x16x32_f16 v[4:7], v[170:173], v[230:233], v[4:7]
	s_barrier
	s_add_i32 s22, s22, 2
	s_add_u32 s14, s14, 0x100
	s_addc_u32 s15, s15, 0
	s_add_u32 s6, s6, 0x2000
	s_addc_u32 s7, s7, 0
	s_cmp_gt_u32 s22, 13
	s_cbranch_scc0 .LBB0_700
	s_and_b64 vcc, exec, s[46:47]
	s_cbranch_vccz .LBB0_703
	s_barrier
